# out-proj: lanes remapped for the channel-major K-steps so the 2-byte LDS transposing scatter is bank-conflict free; hyena loop 3-stage step pipeline
# speedup vs baseline: 1.2337x; 1.0204x over previous
.LBB0_74:
	s_and_b32 s10, s8, 0xffffe00
	v_readlane_b32 s13, v253, 45
	s_or_b32 s10, s13, s10
	s_and_b32 s12, s9, 56
	s_add_i32 s10, s10, s12
	s_lshl_b32 s10, s10, 4
	v_mov_b32_e32 v8, v151
	s_ashr_i32 s11, s10, 31
	s_lshl_b64 s[40:41], s[10:11], 1
	v_bfe_u32 v12, v8, 4, 2
	s_and_b32 s10, s7, 7
	v_and_b32_e32 v9, 63, v8
	v_ashrrev_i32_e32 v11, 6, v8
	v_xor_b32_e32 v0, v12, v8
	s_lshl_b32 s11, s10, 18
	s_lshl_b32 s10, s9, 3
	v_lshl_or_b32 v3, v11, 8, v9
	v_lshlrev_b32_e32 v0, 3, v0
	s_and_b32 s10, s10, 0xfffffe00
	s_or_b32 s12, s12, s13
	v_lshlrev_b32_e32 v2, 7, v3
	v_and_b32_e32 v13, 56, v0
	s_movk_i32 s42, 0x9c00
	s_or_b32 s10, s12, s10
	v_and_or_b32 v0, v2, s42, v13
	v_or_b32_e32 v2, 64, v3
	s_ashr_i32 s12, s10, 3
	v_lshrrev_b32_e32 v4, 4, v2
	s_ashr_i32 s13, s12, 31
	v_xor_b32_e32 v4, v4, v8
	v_or_b32_e32 v3, 0xc0, v3
	s_and_b32 s10, s9, 7
	s_lshl_b64 s[28:29], s[12:13], 17
	s_lshl_b64 s[38:39], s[12:13], 18
	v_lshlrev_b32_e32 v14, 7, v2
	v_lshlrev_b32_e32 v2, 3, v4
	v_lshrrev_b32_e32 v4, 4, v3
	s_add_u32 s12, s94, s38
	v_xor_b32_e32 v4, v4, v8
	v_lshlrev_b32_e32 v122, 12, v11
	s_addc_u32 s13, s95, s39
	s_lshl_b32 s14, s10, 18
	v_lshlrev_b32_e32 v16, 7, v3
	v_lshlrev_b32_e32 v3, 3, v4
	v_lshlrev_b64 v[4:5], 1, v[0:1]
	v_readfirstlane_b32 s16, v122
	v_add_u32_e32 v123, 0x4000, v122
	s_add_u32 s14, s5, s14
	v_lshl_add_u64 v[6:7], s[12:13], 0, v[4:5]
	s_mov_b32 m0, s16
	v_readfirstlane_b32 s16, v123
	s_addc_u32 s15, s6, 0
	v_and_b32_e32 v15, 56, v2
	s_barrier
	global_load_lds_dwordx4 v[6:7], off
	s_mov_b32 m0, s16
	s_movk_i32 s16, 0xbc00
	v_or_b32_e32 v2, 0x4000, v0
	v_lshl_add_u64 v[4:5], s[14:15], 0, v[4:5]
	v_and_or_b32 v0, v14, s16, v15
	global_load_lds_dwordx4 v[4:5], off
	v_lshlrev_b64 v[4:5], 1, v[0:1]
	v_or_b32_e32 v0, 0x400, v122
	v_add_u32_e32 v124, 0x4400, v122
	v_readfirstlane_b32 s16, v0
	v_and_b32_e32 v17, 56, v3
	v_lshl_add_u64 v[6:7], s[12:13], 0, v[4:5]
	s_mov_b32 m0, s16
	v_readfirstlane_b32 s16, v124
	v_mov_b32_e32 v3, v1
	v_or_b32_e32 v0, 0x800, v122
	global_load_lds_dwordx4 v[6:7], off
	v_lshl_add_u64 v[6:7], s[14:15], 0, v[4:5]
	s_mov_b32 m0, s16
	v_lshlrev_b64 v[2:3], 1, v[2:3]
	v_readfirstlane_b32 s16, v0
	v_add_u32_e32 v125, 0x4800, v122
	global_load_lds_dwordx4 v[6:7], off
	v_lshl_add_u64 v[6:7], s[12:13], 0, v[2:3]
	s_mov_b32 m0, s16
	v_readfirstlane_b32 s16, v125
	global_load_lds_dwordx4 v[6:7], off
	s_mov_b32 m0, s16
	v_readlane_b32 s16, v255, 35
	v_readlane_b32 s17, v255, 36
	s_movk_i32 s17, 0xfc00
	v_lshl_add_u64 v[2:3], s[14:15], 0, v[2:3]
	v_and_or_b32 v0, v16, s17, v17
	global_load_lds_dwordx4 v[2:3], off
	v_lshlrev_b64 v[2:3], 1, v[0:1]
	v_or_b32_e32 v0, 0xc00, v122
	v_lshl_add_u64 v[6:7], s[12:13], 0, v[2:3]
	v_readfirstlane_b32 s12, v0
	v_add_u32_e32 v126, 0x4c00, v122
	s_mov_b32 m0, s12
	v_readfirstlane_b32 s12, v126
	global_load_lds_dwordx4 v[6:7], off
	v_lshl_add_u64 v[6:7], s[14:15], 0, v[2:3]
	s_mov_b32 m0, s12
	v_lshrrev_b32_e32 v0, 1, v8
	global_load_lds_dwordx4 v[6:7], off
	v_ashrrev_i32_e32 v10, 7, v8
	v_bitop3_b32 v0, v12, v0, 7 bitop3:0x78
	v_lshlrev_b32_e32 v16, 13, v11
	v_bfe_u32 v6, v8, 1, 3
	v_lshlrev_b32_e32 v0, 4, v0
	v_lshlrev_b32_e32 v7, 13, v10
	v_and_b32_e32 v16, 0x2000, v16
	v_or_b32_e32 v15, v0, v7
	v_or_b32_e32 v17, v0, v16
	v_bitop3_b32 v0, v12, v6, 4 bitop3:0x36
	v_lshlrev_b32_e32 v6, 3, v8
	v_lshlrev_b32_e32 v0, 4, v0
	v_and_b32_e32 v6, 0x78, v6
	v_or_b32_e32 v12, v0, v7
	v_add_u32_e32 v7, 0x100, v8
	s_waitcnt vmcnt(0)
	v_lshlrev_b32_e32 v24, 7, v6
	v_or_b32_e32 v27, 2, v6
	v_or_b32_e32 v30, 3, v6
	v_or_b32_e32 v33, 4, v6
	v_or_b32_e32 v36, 5, v6
	v_or_b32_e32 v39, 6, v6
	v_or_b32_e32 v6, 7, v6
	v_ashrrev_i32_e32 v18, 4, v7
	v_lshlrev_b32_e32 v25, 2, v8
	v_lshlrev_b32_e32 v28, 7, v27
	v_lshrrev_b32_e32 v27, 1, v27
	v_lshlrev_b32_e32 v31, 7, v30
	v_lshrrev_b32_e32 v30, 1, v30
	v_lshlrev_b32_e32 v34, 7, v33
	v_lshrrev_b32_e32 v33, 1, v33
	v_lshlrev_b32_e32 v37, 7, v36
	v_lshrrev_b32_e32 v36, 1, v36
	v_lshlrev_b32_e32 v40, 7, v39
	v_lshrrev_b32_e32 v39, 1, v39
	v_lshlrev_b32_e32 v42, 7, v6
	v_lshrrev_b32_e32 v6, 1, v6
	v_ashrrev_i32_e32 v7, 7, v7
	v_add_u32_e32 v19, 0x200, v8
	v_bitop3_b32 v43, v25, v7, 4 bitop3:0x6c
	v_bitop3_b32 v44, v27, v7, 5 bitop3:0x6c
	v_bitop3_b32 v45, v30, v7, 5 bitop3:0x6c
	v_bitop3_b32 v46, v33, v7, 6 bitop3:0x6c
	v_bitop3_b32 v47, v36, v7, 6 bitop3:0x6c
	v_bitop3_b32 v48, v39, v7, 7 bitop3:0x6c
	v_bitop3_b32 v7, v6, v7, 7 bitop3:0x6c
	v_lshl_add_u32 v49, v7, 4, v42
	v_ashrrev_i32_e32 v7, 7, v19
	v_ashrrev_i32_e32 v20, 4, v19
	v_add_u32_e32 v21, 0x300, v8
	v_bitop3_b32 v19, v25, v7, 4 bitop3:0x6c
	v_bitop3_b32 v50, v27, v7, 5 bitop3:0x6c
	v_bitop3_b32 v51, v30, v7, 5 bitop3:0x6c
	v_bitop3_b32 v52, v33, v7, 6 bitop3:0x6c
	v_bitop3_b32 v53, v36, v7, 6 bitop3:0x6c
	v_bitop3_b32 v54, v39, v7, 7 bitop3:0x6c
	v_bitop3_b32 v7, v6, v7, 7 bitop3:0x6c
	v_lshl_add_u32 v55, v7, 4, v42
	v_ashrrev_i32_e32 v7, 7, v21
	v_ashrrev_i32_e32 v22, 4, v21
	v_bitop3_b32 v26, v25, v10, 4 bitop3:0x6c
	v_bitop3_b32 v21, v25, v7, 4 bitop3:0x6c
	v_lshlrev_b32_e32 v14, 7, v8
	v_or_b32_e32 v16, v0, v16
	v_ashrrev_i32_e32 v0, 4, v8
	v_lshrrev_b32_e32 v23, 3, v8
	v_lshl_add_u32 v26, v26, 4, v24
	v_bitop3_b32 v29, v27, v10, 5 bitop3:0x6c
	v_bitop3_b32 v32, v30, v10, 5 bitop3:0x6c
	v_bitop3_b32 v35, v33, v10, 6 bitop3:0x6c
	v_bitop3_b32 v38, v36, v10, 6 bitop3:0x6c
	v_bitop3_b32 v41, v39, v10, 7 bitop3:0x6c
	v_bitop3_b32 v10, v6, v10, 7 bitop3:0x6c
	v_lshl_add_u32 v43, v43, 4, v24
	v_lshl_add_u32 v19, v19, 4, v24
	v_lshl_add_u32 v21, v21, 4, v24
	v_bitop3_b32 v24, v27, v7, 5 bitop3:0x6c
	v_bitop3_b32 v25, v30, v7, 5 bitop3:0x6c
	v_bitop3_b32 v6, v6, v7, 7 bitop3:0x6c
	s_mov_b32 s14, 0xc000
	v_lshlrev_b32_e32 v8, 4, v8
	v_lshl_add_u32 v29, v29, 4, v28
	v_lshl_add_u32 v32, v32, 4, v31
	v_lshl_add_u32 v44, v44, 4, v28
	v_lshl_add_u32 v45, v45, 4, v31
	v_lshl_add_u32 v50, v50, 4, v28
	v_lshl_add_u32 v51, v51, 4, v31
	v_lshl_add_u32 v24, v24, 4, v28
	v_lshl_add_u32 v25, v25, 4, v31
	v_bitop3_b32 v27, v33, v7, 6 bitop3:0x6c
	v_bitop3_b32 v28, v36, v7, 6 bitop3:0x6c
	v_bitop3_b32 v30, v39, v7, 7 bitop3:0x6c
	v_lshl_add_u32 v31, v6, 4, v42
	v_mad_i64_i32 v[6:7], s[12:13], v22, s14, 0
	v_and_b32_e32 v8, 0xf0, v8
	v_or_b32_e32 v6, v6, v8
	v_lshl_add_u64 v[82:83], v[6:7], 0, s[40:41]
	v_mad_i64_i32 v[6:7], s[12:13], v20, s14, 0
	v_or_b32_e32 v6, v6, v8
	v_lshl_add_u64 v[84:85], v[6:7], 0, s[40:41]
	v_mad_i64_i32 v[6:7], s[12:13], v18, s14, 0
	v_or_b32_e32 v6, v6, v8
	v_lshl_add_u64 v[86:87], v[6:7], 0, s[40:41]
	v_mad_i64_i32 v[6:7], s[12:13], v0, s14, 0
	v_lshlrev_b32_e32 v0, 7, v9
	v_or_b32_e32 v6, v6, v8
	v_lshl_or_b32 v0, v11, 15, v0
	v_lshl_add_u64 v[88:89], v[6:7], 0, s[40:41]
	v_and_or_b32 v6, v0, s42, v13
	s_waitcnt vmcnt(0)
	s_add_u32 s12, s0, s11
	v_or_b32_e32 v0, 0x4000, v6
	v_mov_b32_e32 v7, v1
	v_and_b32_e32 v14, 0x780, v14
	v_and_b32_e32 v23, 14, v23
	v_lshl_add_u32 v35, v35, 4, v34
	v_lshl_add_u32 v38, v38, 4, v37
	v_lshl_add_u32 v41, v41, 4, v40
	v_lshl_add_u32 v10, v10, 4, v42
	v_lshl_add_u32 v46, v46, 4, v34
	v_lshl_add_u32 v47, v47, 4, v37
	v_lshl_add_u32 v48, v48, 4, v40
	v_lshl_add_u32 v52, v52, 4, v34
	v_lshl_add_u32 v53, v53, 4, v37
	v_lshl_add_u32 v54, v54, 4, v40
	v_lshl_add_u32 v27, v27, 4, v34
	v_lshl_add_u32 v28, v28, 4, v37
	v_lshl_add_u32 v30, v30, 4, v40
	s_addc_u32 s13, s1, 0
	v_lshlrev_b64 v[8:9], 1, v[0:1]
	v_lshlrev_b64 v[6:7], 1, v[6:7]
	v_mov_b32_e32 v18, 0
	v_lshl_add_u64 v[90:91], s[12:13], 0, v[2:3]
	v_lshl_add_u64 v[92:93], s[12:13], 0, v[8:9]
	v_lshl_add_u64 v[94:95], s[12:13], 0, v[4:5]
	v_lshl_add_u64 v[96:97], s[12:13], 0, v[6:7]
	v_lshl_add_u64 v[98:99], s[38:39], 0, v[4:5]
	v_lshl_add_u64 v[100:101], s[38:39], 0, v[6:7]
	v_lshl_add_u64 v[102:103], s[38:39], 0, v[8:9]
	v_lshl_add_u64 v[104:105], s[38:39], 0, v[2:3]
	s_mov_b32 s11, 0
	v_add_u32_e32 v0, v15, v14
	v_add_u32_e32 v127, v17, v14
	v_add_u32_e32 v128, v12, v14
	v_add_u32_e32 v129, v16, v14
	v_add_u32_e32 v130, v26, v23
	v_add_u32_e32 v131, v29, v23
	v_add_u32_e32 v132, v32, v23
	v_add_u32_e32 v133, v35, v23
	v_add_u32_e32 v134, v38, v23
	v_add_u32_e32 v135, v41, v23
	v_add_u32_e32 v136, v10, v23
	v_add_u32_e32 v137, v43, v23
	v_add_u32_e32 v138, v44, v23
	v_add_u32_e32 v139, v45, v23
	v_add_u32_e32 v140, v46, v23
	v_add_u32_e32 v141, v47, v23
	v_add_u32_e32 v142, v48, v23
	v_add_u32_e32 v143, v49, v23
	v_add_u32_e32 v144, v19, v23
	v_add_u32_e32 v145, v50, v23
	v_add_u32_e32 v154, v51, v23
	v_add_u32_e32 v155, v52, v23
	v_add_u32_e32 v156, v53, v23
	v_add_u32_e32 v157, v54, v23
	v_add_u32_e32 v158, v55, v23
	v_add_u32_e32 v159, v21, v23
	v_add_u32_e32 v160, v24, v23
	v_add_u32_e32 v161, v25, v23
	v_add_u32_e32 v162, v27, v23
	v_add_u32_e32 v163, v28, v23
	v_add_u32_e32 v164, v30, v23
	v_add_u32_e32 v165, v31, v23
	v_and_b32_e32 v240, 15, v151
	v_lshrrev_b32_e32 v241, 4, v151
	v_sub_u32_e32 v242, v240, v241
	v_mul_i32_i24_e32 v244, 0xbff0, v242
	v_ashrrev_i32_e32 v245, 31, v244
	v_lshl_add_u64 v[82:83], v[82:83], 0, v[244:245]
	v_lshl_add_u64 v[84:85], v[84:85], 0, v[244:245]
	v_lshl_add_u64 v[86:87], v[86:87], 0, v[244:245]
	v_lshl_add_u64 v[88:89], v[88:89], 0, v[244:245]
	v_and_b32_e32 v246, 7, v240
	v_lshlrev_b32_e32 v246, 1, v246
	v_lshl_or_b32 v246, v241, 10, v246
	v_lshrrev_b32_e32 v247, 3, v240
	v_and_b32_e32 v242, 1, v241
	v_lshlrev_b32_e32 v242, 2, v242
	v_add_u32_e32 v243, 0, v247
	v_or_b32_e32 v248, 0, v242
	v_xor_b32_e32 v248, v243, v248
	v_lshl_add_u32 v130, v248, 4, v246
	v_or_b32_e32 v248, 1, v242
	v_xor_b32_e32 v248, v243, v248
	v_lshl_add_u32 v248, v248, 4, v246
	v_add_u32_e32 v131, 0x100, v248
	v_add_u32_e32 v132, 0x180, v248
	v_or_b32_e32 v248, 2, v242
	v_xor_b32_e32 v248, v243, v248
	v_lshl_add_u32 v248, v248, 4, v246
	v_add_u32_e32 v133, 0x200, v248
	v_add_u32_e32 v134, 0x280, v248
	v_or_b32_e32 v248, 3, v242
	v_xor_b32_e32 v248, v243, v248
	v_lshl_add_u32 v248, v248, 4, v246
	v_add_u32_e32 v135, 0x300, v248
	v_add_u32_e32 v136, 0x380, v248
	v_add_u32_e32 v243, 2, v247
	v_or_b32_e32 v248, 0, v242
	v_xor_b32_e32 v248, v243, v248
	v_lshl_add_u32 v137, v248, 4, v246
	v_or_b32_e32 v248, 1, v242
	v_xor_b32_e32 v248, v243, v248
	v_lshl_add_u32 v248, v248, 4, v246
	v_add_u32_e32 v138, 0x100, v248
	v_add_u32_e32 v139, 0x180, v248
	v_or_b32_e32 v248, 2, v242
	v_xor_b32_e32 v248, v243, v248
	v_lshl_add_u32 v248, v248, 4, v246
	v_add_u32_e32 v140, 0x200, v248
	v_add_u32_e32 v141, 0x280, v248
	v_or_b32_e32 v248, 3, v242
	v_xor_b32_e32 v248, v243, v248
	v_lshl_add_u32 v248, v248, 4, v246
	v_add_u32_e32 v142, 0x300, v248
	v_add_u32_e32 v143, 0x380, v248
	v_add_u32_e32 v243, 4, v247
	v_or_b32_e32 v248, 0, v242
	v_xor_b32_e32 v248, v243, v248
	v_lshl_add_u32 v144, v248, 4, v246
	v_or_b32_e32 v248, 1, v242
	v_xor_b32_e32 v248, v243, v248
	v_lshl_add_u32 v248, v248, 4, v246
	v_add_u32_e32 v145, 0x100, v248
	v_add_u32_e32 v154, 0x180, v248
	v_or_b32_e32 v248, 2, v242
	v_xor_b32_e32 v248, v243, v248
	v_lshl_add_u32 v248, v248, 4, v246
	v_add_u32_e32 v155, 0x200, v248
	v_add_u32_e32 v156, 0x280, v248
	v_or_b32_e32 v248, 3, v242
	v_xor_b32_e32 v248, v243, v248
	v_lshl_add_u32 v248, v248, 4, v246
	v_add_u32_e32 v157, 0x300, v248
	v_add_u32_e32 v158, 0x380, v248
	v_add_u32_e32 v243, 6, v247
	v_or_b32_e32 v248, 0, v242
	v_xor_b32_e32 v248, v243, v248
	v_lshl_add_u32 v159, v248, 4, v246
	v_or_b32_e32 v248, 1, v242
	v_xor_b32_e32 v248, v243, v248
	v_lshl_add_u32 v248, v248, 4, v246
	v_add_u32_e32 v160, 0x100, v248
	v_add_u32_e32 v161, 0x180, v248
	v_or_b32_e32 v248, 2, v242
	v_xor_b32_e32 v248, v243, v248
	v_lshl_add_u32 v248, v248, 4, v246
	v_add_u32_e32 v162, 0x200, v248
	v_add_u32_e32 v163, 0x280, v248
	v_or_b32_e32 v248, 3, v242
	v_xor_b32_e32 v248, v243, v248
	v_lshl_add_u32 v248, v248, 4, v246
	v_add_u32_e32 v164, 0x300, v248
	v_add_u32_e32 v165, 0x380, v248
	v_mov_b32_e32 v19, v18
	v_mov_b32_e32 v20, v18
	v_mov_b32_e32 v21, v18
	v_mov_b32_e32 v22, v18
	v_mov_b32_e32 v23, v18
	v_mov_b32_e32 v24, v18
	v_mov_b32_e32 v25, v18
	v_mov_b32_e32 v26, v18
	v_mov_b32_e32 v27, v18
	v_mov_b32_e32 v28, v18
	v_mov_b32_e32 v29, v18
	v_mov_b32_e32 v30, v18
	v_mov_b32_e32 v31, v18
	v_mov_b32_e32 v32, v18
	v_mov_b32_e32 v33, v18
	v_mov_b32_e32 v34, v18
	v_mov_b32_e32 v35, v18
	v_mov_b32_e32 v36, v18
	v_mov_b32_e32 v37, v18
	v_mov_b32_e32 v38, v18
	v_mov_b32_e32 v39, v18
	v_mov_b32_e32 v40, v18
	v_mov_b32_e32 v41, v18
	v_mov_b32_e32 v42, v18
	v_mov_b32_e32 v43, v18
	v_mov_b32_e32 v44, v18
	v_mov_b32_e32 v45, v18
	v_mov_b32_e32 v46, v18
	v_mov_b32_e32 v47, v18
	v_mov_b32_e32 v48, v18
	v_mov_b32_e32 v49, v18
	v_mov_b32_e32 v50, v18
	v_mov_b32_e32 v51, v18
	v_mov_b32_e32 v52, v18
	v_mov_b32_e32 v53, v18
	v_mov_b32_e32 v54, v18
	v_mov_b32_e32 v55, v18
	v_mov_b32_e32 v56, v18
	v_mov_b32_e32 v57, v18
	v_mov_b32_e32 v58, v18
	v_mov_b32_e32 v59, v18
	v_mov_b32_e32 v60, v18
	v_mov_b32_e32 v61, v18
	v_mov_b32_e32 v62, v18
	v_mov_b32_e32 v63, v18
	v_mov_b32_e32 v64, v18
	v_mov_b32_e32 v65, v18
	v_mov_b32_e32 v66, v18
	v_mov_b32_e32 v67, v18
	v_mov_b32_e32 v68, v18
	v_mov_b32_e32 v69, v18
	v_mov_b32_e32 v70, v18
	v_mov_b32_e32 v71, v18
	v_mov_b32_e32 v72, v18
	v_mov_b32_e32 v73, v18
	v_mov_b32_e32 v74, v18
	v_mov_b32_e32 v75, v18
	v_mov_b32_e32 v76, v18
	v_mov_b32_e32 v77, v18
	v_mov_b32_e32 v78, v18
	v_mov_b32_e32 v79, v18
	v_mov_b32_e32 v80, v18
	v_mov_b32_e32 v81, v18
	s_mov_b32 s13, 0x7b00000
	s_mov_b32 s17, 0x7e00000
	s_waitcnt lgkmcnt(0)
	s_barrier
	s_branch .LBB0_76

.LBB0_619:
	s_or_b64 exec, exec, s[28:29]
	s_waitcnt vmcnt(1)
	v_lshlrev_b32_e32 v41, 16, v5
	v_and_b32_e32 v43, 0xffff0000, v5
	s_waitcnt vmcnt(0)
	v_and_b32_e32 v44, 0xffff0000, v8
	v_lshlrev_b32_e32 v5, 16, v8
	v_and_b32_e32 v8, 0xffff0000, v2
	v_lshlrev_b32_e32 v30, 16, v6
	v_and_b32_e32 v6, 0xffff0000, v6
	v_mov_b32_e32 v36, v8
	v_lshrrev_b32_e32 v233, 5, v0
	v_lshlrev_b32_e32 v0, 16, v2
	v_lshlrev_b32_e32 v45, 16, v9
	v_and_b32_e32 v47, 0xffff0000, v9
	v_and_b32_e32 v48, 0xffff0000, v3
	v_lshlrev_b32_e32 v9, 16, v3
	v_pk_mul_f32 v[2:3], v[20:21], v[36:37]
	v_mov_b32_e32 v38, v6
	v_and_b32_e32 v31, 31, v111
	v_pk_fma_f32 v[2:3], v[20:21], v[0:1], v[2:3] op_sel:[0,0,1] op_sel_hi:[1,0,0]
	v_pk_mul_f32 v[20:21], v[18:19], v[38:39]
	v_and_b32_e32 v40, 0xffff0000, v4
	v_lshlrev_b32_e32 v49, 16, v4
	v_and_b32_e32 v4, 0xffff0000, v7
	v_lshlrev_b32_e32 v7, 16, v7
	v_pk_fma_f32 v[18:19], v[18:19], v[30:31], v[20:21] op_sel:[0,0,1] op_sel_hi:[1,0,0]
	v_pk_fma_f32 v[2:3], v[12:13], v[8:9], v[2:3]
	v_pk_fma_f32 v[18:19], v[10:11], v[6:7], v[18:19]
	v_pk_add_f32 v[2:3], v[16:17], v[2:3]
	v_pk_add_f32 v[18:19], v[14:15], v[18:19]
	v_mov_b32_e32 v42, v41
	v_pk_mul_f32 v[2:3], v[2:3], v[18:19]
	v_pk_mov_b32 v[18:19], v[8:9], v[48:49] op_sel:[1,0]
	v_cvt_pk_bf16_f32 v2, v2, v3
	v_pk_mul_f32 v[18:19], v[28:29], v[18:19]
	v_mov_b32_e32 v46, v45
	v_pk_fma_f32 v[8:9], v[24:25], v[8:9], v[18:19]
	v_pk_mov_b32 v[18:19], v[6:7], v[4:5] op_sel:[1,0]
	v_pk_fma_f32 v[8:9], v[12:13], v[48:49], v[8:9]
	v_pk_mul_f32 v[18:19], v[26:27], v[18:19]
	v_pk_add_f32 v[8:9], v[16:17], v[8:9]
	v_pk_fma_f32 v[6:7], v[22:23], v[6:7], v[18:19]
	v_mov_b32_e32 v34, v43
	v_pk_fma_f32 v[6:7], v[10:11], v[4:5], v[6:7]
	v_mov_b32_e32 v32, v47
	v_pk_add_f32 v[6:7], v[14:15], v[6:7]
	v_add_u32_e32 v0, 0x400, v223
	v_pk_mul_f32 v[6:7], v[8:9], v[6:7]
	v_pk_mov_b32 v[8:9], v[4:5], v[44:45] op_sel:[1,0]
	v_cvt_pk_bf16_f32 v3, v6, v7
	v_pk_mov_b32 v[6:7], v[48:49], v[40:41] op_sel:[1,0]
	v_pk_mul_f32 v[8:9], v[26:27], v[8:9]
	v_pk_mul_f32 v[6:7], v[28:29], v[6:7]
	v_pk_fma_f32 v[4:5], v[22:23], v[4:5], v[8:9]
	v_pk_fma_f32 v[6:7], v[24:25], v[48:49], v[6:7]
	v_pk_fma_f32 v[4:5], v[10:11], v[44:45], v[4:5]
	v_pk_fma_f32 v[6:7], v[12:13], v[40:41], v[6:7]
	v_pk_add_f32 v[4:5], v[14:15], v[4:5]
	v_pk_add_f32 v[6:7], v[16:17], v[6:7]
	v_pk_mul_f32 v[8:9], v[26:27], v[46:47]
	v_pk_mul_f32 v[4:5], v[6:7], v[4:5]
	v_pk_mul_f32 v[6:7], v[28:29], v[42:43]
	v_pk_fma_f32 v[8:9], v[22:23], v[44:45], v[8:9]
	v_pk_fma_f32 v[6:7], v[24:25], v[40:41], v[6:7]
	v_pk_fma_f32 v[8:9], v[10:11], v[32:33], v[8:9]
	v_pk_fma_f32 v[6:7], v[12:13], v[34:35], v[6:7]
	v_pk_add_f32 v[8:9], v[14:15], v[8:9]
	v_pk_add_f32 v[6:7], v[16:17], v[6:7]
	v_ashrrev_i32_e32 v0, 1, v0
	v_pk_mul_f32 v[6:7], v[6:7], v[8:9]
	v_cvt_pk_bf16_f32 v4, v4, v5
	v_cvt_pk_bf16_f32 v5, v6, v7
	v_mul_i32_i24_e32 v6, 0x3c00, v222
	v_lshlrev_b32_e32 v226, 1, v223
	v_and_b32_e32 v0, -16, v0
	v_add3_u32 v0, v6, v226, v0
	ds_write_b128 v0, v[2:5] offset:18560
	v_lshlrev_b32_e32 v235, 1, v31
	v_lshlrev_b32_e32 v5, 4, v233
	v_xad_u32 v2, v5, 16, v235
	s_waitcnt lgkmcnt(0)
	s_barrier
	v_lshlrev_b32_e32 v0, 3, v233
	ds_read_b32 v6, v2 offset:14
	v_or_b32_e32 v2, 7, v0
	v_lshlrev_b32_e32 v234, 5, v31
	v_sub_u32_e32 v2, v31, v2
	v_or_b32_e32 v0, v234, v0
	v_lshlrev_b32_e32 v2, 1, v2
	s_movk_i32 s0, 0x1e00
	v_add_u16_e32 v8, 0x13f0, v0
	ds_read_b96 v[2:4], v2 offset:32
	ds_read_b128 v[66:69], v1 offset:16512
	v_mul_lo_u32 v236, v159, s0
	v_lshrrev_b16_e32 v8, 1, v8
	s_waitcnt lgkmcnt(2)
	v_alignbit_b32 v94, v6, v6, 16
	v_lshlrev_b32_e32 v6, 1, v0
	v_lshlrev_b32_e32 v7, 1, v236
	v_and_b32_e32 v8, 0x7ff0, v8
	v_add3_u32 v6, v6, v7, v8
	ds_read_b128 v[70:73], v6 offset:26720
	s_waitcnt lgkmcnt(2)
	v_alignbit_b32 v97, v2, v2, 16
	v_sub_u32_e32 v2, v235, v5
	v_mov_b32_e32 v14, v1
	v_mov_b32_e32 v15, v1
	v_alignbit_b32 v95, v4, v4, 16
	v_alignbit_b32 v96, v3, v3, 16
	v_add_u32_e32 v237, 50, v2
	v_add_u32_e32 v238, 0x13d0, v0
	v_mov_b32_e32 v0, v1
	v_mov_b32_e32 v2, v1
	v_mov_b32_e32 v3, v1
	v_mov_b32_e32 v4, v1
	v_mov_b32_e32 v5, v1
	v_mov_b32_e32 v6, v1
	v_mov_b32_e32 v7, v1
	v_mov_b32_e32 v8, v1
	v_mov_b32_e32 v9, v1
	v_mov_b32_e32 v10, v1
	v_mov_b32_e32 v11, v1
	v_mov_b32_e32 v12, v1
	v_mov_b32_e32 v13, v1
	v_mov_b64_e32 v[64:65], v[14:15]
	v_mov_b64_e32 v[48:49], v[14:15]
	v_mov_b64_e32 v[32:33], v[14:15]
	s_waitcnt lgkmcnt(1)
	v_mov_b64_e32 v[80:81], v[68:69]
	v_mov_b64_e32 v[76:77], v[68:69]
	v_mov_b64_e32 v[62:63], v[12:13]
	v_mov_b64_e32 v[60:61], v[10:11]
	v_mov_b64_e32 v[58:59], v[8:9]
	v_mov_b64_e32 v[56:57], v[6:7]
	v_mov_b64_e32 v[54:55], v[4:5]
	v_mov_b64_e32 v[52:53], v[2:3]
	v_mov_b64_e32 v[50:51], v[0:1]
	v_mov_b64_e32 v[46:47], v[12:13]
	v_mov_b64_e32 v[44:45], v[10:11]
	v_mov_b64_e32 v[42:43], v[8:9]
	v_mov_b64_e32 v[40:41], v[6:7]
	v_mov_b64_e32 v[38:39], v[4:5]
	v_mov_b64_e32 v[36:37], v[2:3]
	v_mov_b64_e32 v[34:35], v[0:1]
	v_mov_b64_e32 v[30:31], v[12:13]
	v_mov_b64_e32 v[28:29], v[10:11]
	v_mov_b64_e32 v[26:27], v[8:9]
	v_mov_b64_e32 v[24:25], v[6:7]
	v_mov_b64_e32 v[22:23], v[4:5]
	v_mov_b64_e32 v[20:21], v[2:3]
	v_mov_b64_e32 v[18:19], v[0:1]
	v_mov_b64_e32 v[16:17], v[14:15]
	s_movk_i32 s5, 0xfeff
	v_mov_b64_e32 v[78:79], v[66:67]
	v_mov_b64_e32 v[74:75], v[66:67]
	v_mov_b64_e32 v[14:15], v[12:13]
	v_mov_b64_e32 v[12:13], v[10:11]
	v_mov_b64_e32 v[10:11], v[8:9]
	v_mov_b64_e32 v[8:9], v[6:7]
	v_mov_b64_e32 v[6:7], v[4:5]
	v_mov_b64_e32 v[4:5], v[2:3]
	v_mov_b64_e32 v[2:3], v[0:1]
	s_waitcnt lgkmcnt(0)
	v_and_b32_e32 v248, 31, v151
	v_bfe_u32 v245, v151, 5, 1
	v_lshrrev_b32_e32 v247, 6, v151
	v_lshlrev_b32_e32 v244, 3, v245
	v_sub_u32_e32 v244, v248, v244
	v_add_u32_e32 v244, 9, v244
	v_and_b32_e32 v249, 1, v244
	v_cmp_eq_u32_e32 vcc, 1, v249
	v_lshrrev_b32_e32 v244, 1, v244
	v_lshlrev_b32_e32 v244, 2, v244
	s_mov_b32 s5, 0xffff
	v_mul_u32_u24_e32 v246, 80, v248
	v_lshl_add_u32 v246, v245, 4, v246
	v_mul_u32_u24_e32 v247, 0x3c00, v247
	v_add_u32_e32 v247, v246, v247
	v_add_u32_e32 v247, 0x7230, v247
	v_add_u32_e32 v246, 32, v247
	v_add_u32_e32 v245, 32, v244
	ds_read2_b32 v[66:67], v244 offset1:1
	ds_read2_b32 v[68:69], v244 offset0:2 offset1:3
	ds_read_b32 v70, v244 offset:16
	v_add_u32_e32 v244, 64, v244
	ds_read_b128 v[76:79], v246 offset:0
	v_add_u32_e32 v246, 0xffffffb0, v246
	ds_read2_b32 v[92:93], v245 offset1:1
	ds_read2_b32 v[94:95], v245 offset0:2 offset1:3
	ds_read_b32 v96, v245 offset:16
	v_add_u32_e32 v245, 64, v245
	s_waitcnt lgkmcnt(3)
	v_alignbit_b32 v72, v69, v69, 16
	v_bfi_b32 v249, s5, v70, v69
	v_cndmask_b32_e32 v72, v72, v249, vcc
	v_alignbit_b32 v73, v68, v68, 16
	v_bfi_b32 v249, s5, v69, v68
	v_cndmask_b32_e32 v73, v73, v249, vcc
	v_alignbit_b32 v74, v67, v67, 16
	v_bfi_b32 v249, s5, v68, v67
	v_cndmask_b32_e32 v74, v74, v249, vcc
	v_alignbit_b32 v75, v66, v66, 16
	v_bfi_b32 v249, s5, v67, v66
	v_cndmask_b32_e32 v75, v75, v249, vcc
	s_mov_b32 s4, 31
.Lhy_seg0:
	ds_read2_b32 v[66:67], v244 offset1:1
	ds_read2_b32 v[68:69], v244 offset0:2 offset1:3
	ds_read_b32 v70, v244 offset:16
	v_add_u32_e32 v244, 64, v244
	ds_read_b128 v[102:105], v247 offset:0
	v_add_u32_e32 v247, 0xffffffb0, v247
	s_waitcnt lgkmcnt(4)
	s_nop 1
	v_mfma_f32_32x32x16_bf16 v[50:65], v[72:75], v[76:79], v[50:65]
	v_alignbit_b32 v98, v95, v95, 16
	v_bfi_b32 v249, s5, v96, v95
	v_cndmask_b32_e32 v98, v98, v249, vcc
	v_alignbit_b32 v99, v94, v94, 16
	v_bfi_b32 v249, s5, v95, v94
	v_cndmask_b32_e32 v99, v99, v249, vcc
	v_alignbit_b32 v100, v93, v93, 16
	v_bfi_b32 v249, s5, v94, v93
	v_cndmask_b32_e32 v100, v100, v249, vcc
	v_alignbit_b32 v101, v92, v92, 16
	v_bfi_b32 v249, s5, v93, v92
	v_cndmask_b32_e32 v101, v101, v249, vcc
	ds_read2_b32 v[92:93], v245 offset1:1
	ds_read2_b32 v[94:95], v245 offset0:2 offset1:3
	ds_read_b32 v96, v245 offset:16
	v_add_u32_e32 v245, 64, v245
	ds_read_b128 v[76:79], v246 offset:0
	v_add_u32_e32 v246, 0xffffffb0, v246
	s_waitcnt lgkmcnt(4)
	s_nop 1
	v_mfma_f32_32x32x16_bf16 v[50:65], v[98:101], v[102:105], v[50:65]
	v_alignbit_b32 v72, v69, v69, 16
	v_bfi_b32 v249, s5, v70, v69
	v_cndmask_b32_e32 v72, v72, v249, vcc
	v_alignbit_b32 v73, v68, v68, 16
	v_bfi_b32 v249, s5, v69, v68
	v_cndmask_b32_e32 v73, v73, v249, vcc
	v_alignbit_b32 v74, v67, v67, 16
	v_bfi_b32 v249, s5, v68, v67
	v_cndmask_b32_e32 v74, v74, v249, vcc
	v_alignbit_b32 v75, v66, v66, 16
	v_bfi_b32 v249, s5, v67, v66
	v_cndmask_b32_e32 v75, v75, v249, vcc
	s_add_i32 s4, s4, -1
	s_cmp_lg_u32 s4, 0
	s_cbranch_scc1 .Lhy_seg0
	ds_read2_b32 v[66:67], v244 offset1:1
	ds_read2_b32 v[68:69], v244 offset0:2 offset1:3
	ds_read_b32 v70, v244 offset:16
	v_add_u32_e32 v244, 64, v244
	ds_read_b128 v[102:105], v247 offset:0
	v_add_u32_e32 v247, 0xffffffb0, v247
	s_waitcnt lgkmcnt(4)
	s_nop 1
	v_mfma_f32_32x32x16_bf16 v[50:65], v[72:75], v[76:79], v[50:65]
	v_alignbit_b32 v98, v95, v95, 16
	v_bfi_b32 v249, s5, v96, v95
	v_cndmask_b32_e32 v98, v98, v249, vcc
	v_alignbit_b32 v99, v94, v94, 16
	v_bfi_b32 v249, s5, v95, v94
	v_cndmask_b32_e32 v99, v99, v249, vcc
	v_alignbit_b32 v100, v93, v93, 16
	v_bfi_b32 v249, s5, v94, v93
	v_cndmask_b32_e32 v100, v100, v249, vcc
	v_alignbit_b32 v101, v92, v92, 16
	v_bfi_b32 v249, s5, v93, v92
	v_cndmask_b32_e32 v101, v101, v249, vcc
	ds_read2_b32 v[92:93], v245 offset1:1
	ds_read2_b32 v[94:95], v245 offset0:2 offset1:3
	ds_read_b32 v96, v245 offset:16
	v_add_u32_e32 v245, 64, v245
	ds_read_b128 v[76:79], v246 offset:0
	ds_read_b128 v[80:83], v246 offset:2560
	v_add_u32_e32 v246, 0xffffffb0, v246
	s_waitcnt lgkmcnt(5)
	s_nop 1
	v_mfma_f32_32x32x16_bf16 v[50:65], v[98:101], v[102:105], v[50:65]
	v_alignbit_b32 v72, v69, v69, 16
	v_bfi_b32 v249, s5, v70, v69
	v_cndmask_b32_e32 v72, v72, v249, vcc
	v_alignbit_b32 v73, v68, v68, 16
	v_bfi_b32 v249, s5, v69, v68
	v_cndmask_b32_e32 v73, v73, v249, vcc
	v_alignbit_b32 v74, v67, v67, 16
	v_bfi_b32 v249, s5, v68, v67
	v_cndmask_b32_e32 v74, v74, v249, vcc
	v_alignbit_b32 v75, v66, v66, 16
	v_bfi_b32 v249, s5, v67, v66
	v_cndmask_b32_e32 v75, v75, v249, vcc
	s_mov_b32 s4, 31
.Lhy_seg1:
	ds_read2_b32 v[66:67], v244 offset1:1
	ds_read2_b32 v[68:69], v244 offset0:2 offset1:3
	ds_read_b32 v70, v244 offset:16
	v_add_u32_e32 v244, 64, v244
	ds_read_b128 v[102:105], v247 offset:0
	ds_read_b128 v[106:109], v247 offset:2560
	v_add_u32_e32 v247, 0xffffffb0, v247
	s_waitcnt lgkmcnt(5)
	s_nop 1
	v_mfma_f32_32x32x16_bf16 v[50:65], v[72:75], v[76:79], v[50:65]
	v_alignbit_b32 v98, v95, v95, 16
	v_bfi_b32 v249, s5, v96, v95
	v_cndmask_b32_e32 v98, v98, v249, vcc
	v_alignbit_b32 v99, v94, v94, 16
	v_bfi_b32 v249, s5, v95, v94
	v_cndmask_b32_e32 v99, v99, v249, vcc
	v_mfma_f32_32x32x16_bf16 v[34:49], v[72:75], v[80:83], v[34:49]
	v_alignbit_b32 v100, v93, v93, 16
	v_bfi_b32 v249, s5, v94, v93
	v_cndmask_b32_e32 v100, v100, v249, vcc
	v_alignbit_b32 v101, v92, v92, 16
	v_bfi_b32 v249, s5, v93, v92
	v_cndmask_b32_e32 v101, v101, v249, vcc
	ds_read2_b32 v[92:93], v245 offset1:1
	ds_read2_b32 v[94:95], v245 offset0:2 offset1:3
	ds_read_b32 v96, v245 offset:16
	v_add_u32_e32 v245, 64, v245
	ds_read_b128 v[76:79], v246 offset:0
	ds_read_b128 v[80:83], v246 offset:2560
	v_add_u32_e32 v246, 0xffffffb0, v246
	s_waitcnt lgkmcnt(5)
	s_nop 1
	v_mfma_f32_32x32x16_bf16 v[50:65], v[98:101], v[102:105], v[50:65]
	v_alignbit_b32 v72, v69, v69, 16
	v_bfi_b32 v249, s5, v70, v69
	v_cndmask_b32_e32 v72, v72, v249, vcc
	v_alignbit_b32 v73, v68, v68, 16
	v_bfi_b32 v249, s5, v69, v68
	v_cndmask_b32_e32 v73, v73, v249, vcc
	v_mfma_f32_32x32x16_bf16 v[34:49], v[98:101], v[106:109], v[34:49]
	v_alignbit_b32 v74, v67, v67, 16
	v_bfi_b32 v249, s5, v68, v67
	v_cndmask_b32_e32 v74, v74, v249, vcc
	v_alignbit_b32 v75, v66, v66, 16
	v_bfi_b32 v249, s5, v67, v66
	v_cndmask_b32_e32 v75, v75, v249, vcc
	s_add_i32 s4, s4, -1
	s_cmp_lg_u32 s4, 0
	s_cbranch_scc1 .Lhy_seg1
	ds_read2_b32 v[66:67], v244 offset1:1
	ds_read2_b32 v[68:69], v244 offset0:2 offset1:3
	ds_read_b32 v70, v244 offset:16
	v_add_u32_e32 v244, 64, v244
	ds_read_b128 v[102:105], v247 offset:0
	ds_read_b128 v[106:109], v247 offset:2560
	v_add_u32_e32 v247, 0xffffffb0, v247
	s_waitcnt lgkmcnt(5)
	s_nop 1
	v_mfma_f32_32x32x16_bf16 v[50:65], v[72:75], v[76:79], v[50:65]
	v_alignbit_b32 v98, v95, v95, 16
	v_bfi_b32 v249, s5, v96, v95
	v_cndmask_b32_e32 v98, v98, v249, vcc
	v_alignbit_b32 v99, v94, v94, 16
	v_bfi_b32 v249, s5, v95, v94
	v_cndmask_b32_e32 v99, v99, v249, vcc
	v_mfma_f32_32x32x16_bf16 v[34:49], v[72:75], v[80:83], v[34:49]
	v_alignbit_b32 v100, v93, v93, 16
	v_bfi_b32 v249, s5, v94, v93
	v_cndmask_b32_e32 v100, v100, v249, vcc
	v_alignbit_b32 v101, v92, v92, 16
	v_bfi_b32 v249, s5, v93, v92
	v_cndmask_b32_e32 v101, v101, v249, vcc
	ds_read2_b32 v[92:93], v245 offset1:1
	ds_read2_b32 v[94:95], v245 offset0:2 offset1:3
	ds_read_b32 v96, v245 offset:16
	v_add_u32_e32 v245, 64, v245
	ds_read_b128 v[76:79], v246 offset:0
	ds_read_b128 v[80:83], v246 offset:2560
	ds_read_b128 v[84:87], v246 offset:5120
	v_add_u32_e32 v246, 0xffffffb0, v246
	s_waitcnt lgkmcnt(6)
	s_nop 1
	v_mfma_f32_32x32x16_bf16 v[50:65], v[98:101], v[102:105], v[50:65]
	v_alignbit_b32 v72, v69, v69, 16
	v_bfi_b32 v249, s5, v70, v69
	v_cndmask_b32_e32 v72, v72, v249, vcc
	v_alignbit_b32 v73, v68, v68, 16
	v_bfi_b32 v249, s5, v69, v68
	v_cndmask_b32_e32 v73, v73, v249, vcc
	v_mfma_f32_32x32x16_bf16 v[34:49], v[98:101], v[106:109], v[34:49]
	v_alignbit_b32 v74, v67, v67, 16
	v_bfi_b32 v249, s5, v68, v67
	v_cndmask_b32_e32 v74, v74, v249, vcc
	v_alignbit_b32 v75, v66, v66, 16
	v_bfi_b32 v249, s5, v67, v66
	v_cndmask_b32_e32 v75, v75, v249, vcc
	s_mov_b32 s4, 31
.Lhy_seg2:
	ds_read2_b32 v[66:67], v244 offset1:1
	ds_read2_b32 v[68:69], v244 offset0:2 offset1:3
	ds_read_b32 v70, v244 offset:16
	v_add_u32_e32 v244, 64, v244
	ds_read_b128 v[102:105], v247 offset:0
	ds_read_b128 v[106:109], v247 offset:2560
	ds_read_b128 v[236:239], v247 offset:5120
	v_add_u32_e32 v247, 0xffffffb0, v247
	s_waitcnt lgkmcnt(6)
	s_nop 1
	v_mfma_f32_32x32x16_bf16 v[50:65], v[72:75], v[76:79], v[50:65]
	v_alignbit_b32 v98, v95, v95, 16
	v_bfi_b32 v249, s5, v96, v95
	v_cndmask_b32_e32 v98, v98, v249, vcc
	v_alignbit_b32 v99, v94, v94, 16
	v_mfma_f32_32x32x16_bf16 v[34:49], v[72:75], v[80:83], v[34:49]
	v_bfi_b32 v249, s5, v95, v94
	v_cndmask_b32_e32 v99, v99, v249, vcc
	v_alignbit_b32 v100, v93, v93, 16
	v_bfi_b32 v249, s5, v94, v93
	v_mfma_f32_32x32x16_bf16 v[18:33], v[72:75], v[84:87], v[18:33]
	v_cndmask_b32_e32 v100, v100, v249, vcc
	v_alignbit_b32 v101, v92, v92, 16
	v_bfi_b32 v249, s5, v93, v92
	v_cndmask_b32_e32 v101, v101, v249, vcc
	ds_read2_b32 v[92:93], v245 offset1:1
	ds_read2_b32 v[94:95], v245 offset0:2 offset1:3
	ds_read_b32 v96, v245 offset:16
	v_add_u32_e32 v245, 64, v245
	ds_read_b128 v[76:79], v246 offset:0
	ds_read_b128 v[80:83], v246 offset:2560
	ds_read_b128 v[84:87], v246 offset:5120
	v_add_u32_e32 v246, 0xffffffb0, v246
	s_waitcnt lgkmcnt(6)
	s_nop 1
	v_mfma_f32_32x32x16_bf16 v[50:65], v[98:101], v[102:105], v[50:65]
	v_alignbit_b32 v72, v69, v69, 16
	v_bfi_b32 v249, s5, v70, v69
	v_cndmask_b32_e32 v72, v72, v249, vcc
	v_alignbit_b32 v73, v68, v68, 16
	v_mfma_f32_32x32x16_bf16 v[34:49], v[98:101], v[106:109], v[34:49]
	v_bfi_b32 v249, s5, v69, v68
	v_cndmask_b32_e32 v73, v73, v249, vcc
	v_alignbit_b32 v74, v67, v67, 16
	v_bfi_b32 v249, s5, v68, v67
	v_mfma_f32_32x32x16_bf16 v[18:33], v[98:101], v[236:239], v[18:33]
	v_cndmask_b32_e32 v74, v74, v249, vcc
	v_alignbit_b32 v75, v66, v66, 16
	v_bfi_b32 v249, s5, v67, v66
	v_cndmask_b32_e32 v75, v75, v249, vcc
	s_add_i32 s4, s4, -1
	s_cmp_lg_u32 s4, 0
	s_cbranch_scc1 .Lhy_seg2
	ds_read2_b32 v[66:67], v244 offset1:1
	ds_read2_b32 v[68:69], v244 offset0:2 offset1:3
	ds_read_b32 v70, v244 offset:16
	v_add_u32_e32 v244, 64, v244
	ds_read_b128 v[102:105], v247 offset:0
	ds_read_b128 v[106:109], v247 offset:2560
	ds_read_b128 v[236:239], v247 offset:5120
	v_add_u32_e32 v247, 0xffffffb0, v247
	s_waitcnt lgkmcnt(6)
	s_nop 1
	v_mfma_f32_32x32x16_bf16 v[50:65], v[72:75], v[76:79], v[50:65]
	v_alignbit_b32 v98, v95, v95, 16
	v_bfi_b32 v249, s5, v96, v95
	v_cndmask_b32_e32 v98, v98, v249, vcc
	v_alignbit_b32 v99, v94, v94, 16
	v_mfma_f32_32x32x16_bf16 v[34:49], v[72:75], v[80:83], v[34:49]
	v_bfi_b32 v249, s5, v95, v94
	v_cndmask_b32_e32 v99, v99, v249, vcc
	v_alignbit_b32 v100, v93, v93, 16
	v_bfi_b32 v249, s5, v94, v93
	v_mfma_f32_32x32x16_bf16 v[18:33], v[72:75], v[84:87], v[18:33]
	v_cndmask_b32_e32 v100, v100, v249, vcc
	v_alignbit_b32 v101, v92, v92, 16
	v_bfi_b32 v249, s5, v93, v92
	v_cndmask_b32_e32 v101, v101, v249, vcc
	ds_read2_b32 v[92:93], v245 offset1:1
	ds_read2_b32 v[94:95], v245 offset0:2 offset1:3
	ds_read_b32 v96, v245 offset:16
	v_add_u32_e32 v245, 64, v245
	ds_read_b128 v[76:79], v246 offset:0
	ds_read_b128 v[80:83], v246 offset:2560
	ds_read_b128 v[84:87], v246 offset:5120
	ds_read_b128 v[88:91], v246 offset:7680
	v_add_u32_e32 v246, 0xffffffb0, v246
	s_waitcnt lgkmcnt(7)
	s_nop 1
	v_mfma_f32_32x32x16_bf16 v[50:65], v[98:101], v[102:105], v[50:65]
	v_alignbit_b32 v72, v69, v69, 16
	v_bfi_b32 v249, s5, v70, v69
	v_cndmask_b32_e32 v72, v72, v249, vcc
	v_alignbit_b32 v73, v68, v68, 16
	v_mfma_f32_32x32x16_bf16 v[34:49], v[98:101], v[106:109], v[34:49]
	v_bfi_b32 v249, s5, v69, v68
	v_cndmask_b32_e32 v73, v73, v249, vcc
	v_alignbit_b32 v74, v67, v67, 16
	v_bfi_b32 v249, s5, v68, v67
	v_mfma_f32_32x32x16_bf16 v[18:33], v[98:101], v[236:239], v[18:33]
	v_cndmask_b32_e32 v74, v74, v249, vcc
	v_alignbit_b32 v75, v66, v66, 16
	v_bfi_b32 v249, s5, v67, v66
	v_cndmask_b32_e32 v75, v75, v249, vcc
	s_mov_b32 s4, 62
.Lhy_seg3:
	ds_read2_b32 v[66:67], v244 offset1:1
	ds_read2_b32 v[68:69], v244 offset0:2 offset1:3
	ds_read_b32 v70, v244 offset:16
	v_add_u32_e32 v244, 64, v244
	ds_read_b128 v[102:105], v247 offset:0
	ds_read_b128 v[106:109], v247 offset:2560
	ds_read_b128 v[236:239], v247 offset:5120
	ds_read_b128 v[240:243], v247 offset:7680
	v_add_u32_e32 v247, 0xffffffb0, v247
	s_waitcnt lgkmcnt(7)
	s_nop 1
	v_mfma_f32_32x32x16_bf16 v[50:65], v[72:75], v[76:79], v[50:65]
	v_alignbit_b32 v98, v95, v95, 16
	v_bfi_b32 v249, s5, v96, v95
	v_cndmask_b32_e32 v98, v98, v249, vcc
	v_mfma_f32_32x32x16_bf16 v[34:49], v[72:75], v[80:83], v[34:49]
	v_alignbit_b32 v99, v94, v94, 16
	v_bfi_b32 v249, s5, v95, v94
	v_cndmask_b32_e32 v99, v99, v249, vcc
	v_mfma_f32_32x32x16_bf16 v[18:33], v[72:75], v[84:87], v[18:33]
	v_alignbit_b32 v100, v93, v93, 16
	v_bfi_b32 v249, s5, v94, v93
	v_cndmask_b32_e32 v100, v100, v249, vcc
	v_mfma_f32_32x32x16_bf16 v[2:17], v[72:75], v[88:91], v[2:17]
	v_alignbit_b32 v101, v92, v92, 16
	v_bfi_b32 v249, s5, v93, v92
	v_cndmask_b32_e32 v101, v101, v249, vcc
	ds_read2_b32 v[92:93], v245 offset1:1
	ds_read2_b32 v[94:95], v245 offset0:2 offset1:3
	ds_read_b32 v96, v245 offset:16
	v_add_u32_e32 v245, 64, v245
	ds_read_b128 v[76:79], v246 offset:0
	ds_read_b128 v[80:83], v246 offset:2560
	ds_read_b128 v[84:87], v246 offset:5120
	ds_read_b128 v[88:91], v246 offset:7680
	v_add_u32_e32 v246, 0xffffffb0, v246
	s_waitcnt lgkmcnt(7)
	s_nop 1
	v_mfma_f32_32x32x16_bf16 v[50:65], v[98:101], v[102:105], v[50:65]
	v_alignbit_b32 v72, v69, v69, 16
	v_bfi_b32 v249, s5, v70, v69
	v_cndmask_b32_e32 v72, v72, v249, vcc
	v_mfma_f32_32x32x16_bf16 v[34:49], v[98:101], v[106:109], v[34:49]
	v_alignbit_b32 v73, v68, v68, 16
	v_bfi_b32 v249, s5, v69, v68
	v_cndmask_b32_e32 v73, v73, v249, vcc
	v_mfma_f32_32x32x16_bf16 v[18:33], v[98:101], v[236:239], v[18:33]
	v_alignbit_b32 v74, v67, v67, 16
	v_bfi_b32 v249, s5, v68, v67
	v_cndmask_b32_e32 v74, v74, v249, vcc
	v_mfma_f32_32x32x16_bf16 v[2:17], v[98:101], v[240:243], v[2:17]
	v_alignbit_b32 v75, v66, v66, 16
	v_bfi_b32 v249, s5, v67, v66
	v_cndmask_b32_e32 v75, v75, v249, vcc
	s_add_i32 s4, s4, -1
	s_cmp_lg_u32 s4, 0
	s_cbranch_scc1 .Lhy_seg3
	ds_read2_b32 v[66:67], v244 offset1:1
	ds_read2_b32 v[68:69], v244 offset0:2 offset1:3
	ds_read_b32 v70, v244 offset:16
	v_add_u32_e32 v244, 64, v244
	ds_read_b128 v[102:105], v247 offset:0
	ds_read_b128 v[106:109], v247 offset:2560
	ds_read_b128 v[236:239], v247 offset:5120
	ds_read_b128 v[240:243], v247 offset:7680
	v_add_u32_e32 v247, 0xffffffb0, v247
	s_waitcnt lgkmcnt(7)
	s_nop 1
	v_mfma_f32_32x32x16_bf16 v[50:65], v[72:75], v[76:79], v[50:65]
	v_alignbit_b32 v98, v95, v95, 16
	v_bfi_b32 v249, s5, v96, v95
	v_cndmask_b32_e32 v98, v98, v249, vcc
	v_mfma_f32_32x32x16_bf16 v[34:49], v[72:75], v[80:83], v[34:49]
	v_alignbit_b32 v99, v94, v94, 16
	v_bfi_b32 v249, s5, v95, v94
	v_cndmask_b32_e32 v99, v99, v249, vcc
	v_mfma_f32_32x32x16_bf16 v[18:33], v[72:75], v[84:87], v[18:33]
	v_alignbit_b32 v100, v93, v93, 16
	v_bfi_b32 v249, s5, v94, v93
	v_cndmask_b32_e32 v100, v100, v249, vcc
	v_mfma_f32_32x32x16_bf16 v[2:17], v[72:75], v[88:91], v[2:17]
	v_alignbit_b32 v101, v92, v92, 16
	v_bfi_b32 v249, s5, v93, v92
	v_cndmask_b32_e32 v101, v101, v249, vcc
	ds_read2_b32 v[92:93], v245 offset1:1
	ds_read2_b32 v[94:95], v245 offset0:2 offset1:3
	ds_read_b32 v96, v245 offset:16
	v_add_u32_e32 v245, 64, v245
	ds_read_b128 v[80:83], v246 offset:2560
	ds_read_b128 v[84:87], v246 offset:5120
	ds_read_b128 v[88:91], v246 offset:7680
	v_add_u32_e32 v246, 0xffffffb0, v246
	s_waitcnt lgkmcnt(6)
	s_nop 1
	v_mfma_f32_32x32x16_bf16 v[50:65], v[98:101], v[102:105], v[50:65]
	v_alignbit_b32 v72, v69, v69, 16
	v_bfi_b32 v249, s5, v70, v69
	v_cndmask_b32_e32 v72, v72, v249, vcc
	v_mfma_f32_32x32x16_bf16 v[34:49], v[98:101], v[106:109], v[34:49]
	v_alignbit_b32 v73, v68, v68, 16
	v_bfi_b32 v249, s5, v69, v68
	v_cndmask_b32_e32 v73, v73, v249, vcc
	v_mfma_f32_32x32x16_bf16 v[18:33], v[98:101], v[236:239], v[18:33]
	v_alignbit_b32 v74, v67, v67, 16
	v_bfi_b32 v249, s5, v68, v67
	v_cndmask_b32_e32 v74, v74, v249, vcc
	v_mfma_f32_32x32x16_bf16 v[2:17], v[98:101], v[240:243], v[2:17]
	v_alignbit_b32 v75, v66, v66, 16
	v_bfi_b32 v249, s5, v67, v66
	v_cndmask_b32_e32 v75, v75, v249, vcc
	s_mov_b32 s4, 31
.Lhy_seg4:
	ds_read2_b32 v[66:67], v244 offset1:1
	ds_read2_b32 v[68:69], v244 offset0:2 offset1:3
	ds_read_b32 v70, v244 offset:16
	v_add_u32_e32 v244, 64, v244
	ds_read_b128 v[106:109], v247 offset:2560
	ds_read_b128 v[236:239], v247 offset:5120
	ds_read_b128 v[240:243], v247 offset:7680
	v_add_u32_e32 v247, 0xffffffb0, v247
	s_waitcnt lgkmcnt(6)
	s_nop 1
	v_mfma_f32_32x32x16_bf16 v[34:49], v[72:75], v[80:83], v[34:49]
	v_alignbit_b32 v98, v95, v95, 16
	v_bfi_b32 v249, s5, v96, v95
	v_cndmask_b32_e32 v98, v98, v249, vcc
	v_alignbit_b32 v99, v94, v94, 16
	v_mfma_f32_32x32x16_bf16 v[18:33], v[72:75], v[84:87], v[18:33]
	v_bfi_b32 v249, s5, v95, v94
	v_cndmask_b32_e32 v99, v99, v249, vcc
	v_alignbit_b32 v100, v93, v93, 16
	v_bfi_b32 v249, s5, v94, v93
	v_mfma_f32_32x32x16_bf16 v[2:17], v[72:75], v[88:91], v[2:17]
	v_cndmask_b32_e32 v100, v100, v249, vcc
	v_alignbit_b32 v101, v92, v92, 16
	v_bfi_b32 v249, s5, v93, v92
	v_cndmask_b32_e32 v101, v101, v249, vcc
	ds_read2_b32 v[92:93], v245 offset1:1
	ds_read2_b32 v[94:95], v245 offset0:2 offset1:3
	ds_read_b32 v96, v245 offset:16
	v_add_u32_e32 v245, 64, v245
	ds_read_b128 v[80:83], v246 offset:2560
	ds_read_b128 v[84:87], v246 offset:5120
	ds_read_b128 v[88:91], v246 offset:7680
	v_add_u32_e32 v246, 0xffffffb0, v246
	s_waitcnt lgkmcnt(6)
	s_nop 1
	v_mfma_f32_32x32x16_bf16 v[34:49], v[98:101], v[106:109], v[34:49]
	v_alignbit_b32 v72, v69, v69, 16
	v_bfi_b32 v249, s5, v70, v69
	v_cndmask_b32_e32 v72, v72, v249, vcc
	v_alignbit_b32 v73, v68, v68, 16
	v_mfma_f32_32x32x16_bf16 v[18:33], v[98:101], v[236:239], v[18:33]
	v_bfi_b32 v249, s5, v69, v68
	v_cndmask_b32_e32 v73, v73, v249, vcc
	v_alignbit_b32 v74, v67, v67, 16
	v_bfi_b32 v249, s5, v68, v67
	v_mfma_f32_32x32x16_bf16 v[2:17], v[98:101], v[240:243], v[2:17]
	v_cndmask_b32_e32 v74, v74, v249, vcc
	v_alignbit_b32 v75, v66, v66, 16
	v_bfi_b32 v249, s5, v67, v66
	v_cndmask_b32_e32 v75, v75, v249, vcc
	s_add_i32 s4, s4, -1
	s_cmp_lg_u32 s4, 0
	s_cbranch_scc1 .Lhy_seg4
	ds_read2_b32 v[66:67], v244 offset1:1
	ds_read2_b32 v[68:69], v244 offset0:2 offset1:3
	ds_read_b32 v70, v244 offset:16
	v_add_u32_e32 v244, 64, v244
	ds_read_b128 v[106:109], v247 offset:2560
	ds_read_b128 v[236:239], v247 offset:5120
	ds_read_b128 v[240:243], v247 offset:7680
	v_add_u32_e32 v247, 0xffffffb0, v247
	s_waitcnt lgkmcnt(6)
	s_nop 1
	v_mfma_f32_32x32x16_bf16 v[34:49], v[72:75], v[80:83], v[34:49]
	v_alignbit_b32 v98, v95, v95, 16
	v_bfi_b32 v249, s5, v96, v95
	v_cndmask_b32_e32 v98, v98, v249, vcc
	v_alignbit_b32 v99, v94, v94, 16
	v_mfma_f32_32x32x16_bf16 v[18:33], v[72:75], v[84:87], v[18:33]
	v_bfi_b32 v249, s5, v95, v94
	v_cndmask_b32_e32 v99, v99, v249, vcc
	v_alignbit_b32 v100, v93, v93, 16
	v_bfi_b32 v249, s5, v94, v93
	v_mfma_f32_32x32x16_bf16 v[2:17], v[72:75], v[88:91], v[2:17]
	v_cndmask_b32_e32 v100, v100, v249, vcc
	v_alignbit_b32 v101, v92, v92, 16
	v_bfi_b32 v249, s5, v93, v92
	v_cndmask_b32_e32 v101, v101, v249, vcc
	ds_read2_b32 v[92:93], v245 offset1:1
	ds_read2_b32 v[94:95], v245 offset0:2 offset1:3
	ds_read_b32 v96, v245 offset:16
	v_add_u32_e32 v245, 64, v245
	ds_read_b128 v[84:87], v246 offset:5120
	ds_read_b128 v[88:91], v246 offset:7680
	v_add_u32_e32 v246, 0xffffffb0, v246
	s_waitcnt lgkmcnt(5)
	s_nop 1
	v_mfma_f32_32x32x16_bf16 v[34:49], v[98:101], v[106:109], v[34:49]
	v_alignbit_b32 v72, v69, v69, 16
	v_bfi_b32 v249, s5, v70, v69
	v_cndmask_b32_e32 v72, v72, v249, vcc
	v_alignbit_b32 v73, v68, v68, 16
	v_mfma_f32_32x32x16_bf16 v[18:33], v[98:101], v[236:239], v[18:33]
	v_bfi_b32 v249, s5, v69, v68
	v_cndmask_b32_e32 v73, v73, v249, vcc
	v_alignbit_b32 v74, v67, v67, 16
	v_bfi_b32 v249, s5, v68, v67
	v_mfma_f32_32x32x16_bf16 v[2:17], v[98:101], v[240:243], v[2:17]
	v_cndmask_b32_e32 v74, v74, v249, vcc
	v_alignbit_b32 v75, v66, v66, 16
	v_bfi_b32 v249, s5, v67, v66
	v_cndmask_b32_e32 v75, v75, v249, vcc
	s_mov_b32 s4, 31
.Lhy_seg5:
	ds_read2_b32 v[66:67], v244 offset1:1
	ds_read2_b32 v[68:69], v244 offset0:2 offset1:3
	ds_read_b32 v70, v244 offset:16
	v_add_u32_e32 v244, 64, v244
	ds_read_b128 v[236:239], v247 offset:5120
	ds_read_b128 v[240:243], v247 offset:7680
	v_add_u32_e32 v247, 0xffffffb0, v247
	s_waitcnt lgkmcnt(5)
	s_nop 1
	v_mfma_f32_32x32x16_bf16 v[18:33], v[72:75], v[84:87], v[18:33]
	v_alignbit_b32 v98, v95, v95, 16
	v_bfi_b32 v249, s5, v96, v95
	v_cndmask_b32_e32 v98, v98, v249, vcc
	v_alignbit_b32 v99, v94, v94, 16
	v_bfi_b32 v249, s5, v95, v94
	v_cndmask_b32_e32 v99, v99, v249, vcc
	v_mfma_f32_32x32x16_bf16 v[2:17], v[72:75], v[88:91], v[2:17]
	v_alignbit_b32 v100, v93, v93, 16
	v_bfi_b32 v249, s5, v94, v93
	v_cndmask_b32_e32 v100, v100, v249, vcc
	v_alignbit_b32 v101, v92, v92, 16
	v_bfi_b32 v249, s5, v93, v92
	v_cndmask_b32_e32 v101, v101, v249, vcc
	ds_read2_b32 v[92:93], v245 offset1:1
	ds_read2_b32 v[94:95], v245 offset0:2 offset1:3
	ds_read_b32 v96, v245 offset:16
	v_add_u32_e32 v245, 64, v245
	ds_read_b128 v[84:87], v246 offset:5120
	ds_read_b128 v[88:91], v246 offset:7680
	v_add_u32_e32 v246, 0xffffffb0, v246
	s_waitcnt lgkmcnt(5)
	s_nop 1
	v_mfma_f32_32x32x16_bf16 v[18:33], v[98:101], v[236:239], v[18:33]
	v_alignbit_b32 v72, v69, v69, 16
	v_bfi_b32 v249, s5, v70, v69
	v_cndmask_b32_e32 v72, v72, v249, vcc
	v_alignbit_b32 v73, v68, v68, 16
	v_bfi_b32 v249, s5, v69, v68
	v_cndmask_b32_e32 v73, v73, v249, vcc
	v_mfma_f32_32x32x16_bf16 v[2:17], v[98:101], v[240:243], v[2:17]
	v_alignbit_b32 v74, v67, v67, 16
	v_bfi_b32 v249, s5, v68, v67
	v_cndmask_b32_e32 v74, v74, v249, vcc
	v_alignbit_b32 v75, v66, v66, 16
	v_bfi_b32 v249, s5, v67, v66
	v_cndmask_b32_e32 v75, v75, v249, vcc
	s_add_i32 s4, s4, -1
	s_cmp_lg_u32 s4, 0
	s_cbranch_scc1 .Lhy_seg5
	ds_read2_b32 v[66:67], v244 offset1:1
	ds_read2_b32 v[68:69], v244 offset0:2 offset1:3
	ds_read_b32 v70, v244 offset:16
	v_add_u32_e32 v244, 64, v244
	ds_read_b128 v[236:239], v247 offset:5120
	ds_read_b128 v[240:243], v247 offset:7680
	v_add_u32_e32 v247, 0xffffffb0, v247
	s_waitcnt lgkmcnt(5)
	s_nop 1
	v_mfma_f32_32x32x16_bf16 v[18:33], v[72:75], v[84:87], v[18:33]
	v_alignbit_b32 v98, v95, v95, 16
	v_bfi_b32 v249, s5, v96, v95
	v_cndmask_b32_e32 v98, v98, v249, vcc
	v_alignbit_b32 v99, v94, v94, 16
	v_bfi_b32 v249, s5, v95, v94
	v_cndmask_b32_e32 v99, v99, v249, vcc
	v_mfma_f32_32x32x16_bf16 v[2:17], v[72:75], v[88:91], v[2:17]
	v_alignbit_b32 v100, v93, v93, 16
	v_bfi_b32 v249, s5, v94, v93
	v_cndmask_b32_e32 v100, v100, v249, vcc
	v_alignbit_b32 v101, v92, v92, 16
	v_bfi_b32 v249, s5, v93, v92
	v_cndmask_b32_e32 v101, v101, v249, vcc
	ds_read2_b32 v[92:93], v245 offset1:1
	ds_read2_b32 v[94:95], v245 offset0:2 offset1:3
	ds_read_b32 v96, v245 offset:16
	v_add_u32_e32 v245, 64, v245
	ds_read_b128 v[88:91], v246 offset:7680
	v_add_u32_e32 v246, 0xffffffb0, v246
	s_waitcnt lgkmcnt(4)
	s_nop 1
	v_mfma_f32_32x32x16_bf16 v[18:33], v[98:101], v[236:239], v[18:33]
	v_alignbit_b32 v72, v69, v69, 16
	v_bfi_b32 v249, s5, v70, v69
	v_cndmask_b32_e32 v72, v72, v249, vcc
	v_alignbit_b32 v73, v68, v68, 16
	v_bfi_b32 v249, s5, v69, v68
	v_cndmask_b32_e32 v73, v73, v249, vcc
	v_mfma_f32_32x32x16_bf16 v[2:17], v[98:101], v[240:243], v[2:17]
	v_alignbit_b32 v74, v67, v67, 16
	v_bfi_b32 v249, s5, v68, v67
	v_cndmask_b32_e32 v74, v74, v249, vcc
	v_alignbit_b32 v75, v66, v66, 16
	v_bfi_b32 v249, s5, v67, v66
	v_cndmask_b32_e32 v75, v75, v249, vcc
	s_mov_b32 s4, 31
.Lhy_seg6:
	ds_read2_b32 v[66:67], v244 offset1:1
	ds_read2_b32 v[68:69], v244 offset0:2 offset1:3
	ds_read_b32 v70, v244 offset:16
	v_add_u32_e32 v244, 64, v244
	ds_read_b128 v[240:243], v247 offset:7680
	v_add_u32_e32 v247, 0xffffffb0, v247
	s_waitcnt lgkmcnt(4)
	s_nop 1
	v_mfma_f32_32x32x16_bf16 v[2:17], v[72:75], v[88:91], v[2:17]
	v_alignbit_b32 v98, v95, v95, 16
	v_bfi_b32 v249, s5, v96, v95
	v_cndmask_b32_e32 v98, v98, v249, vcc
	v_alignbit_b32 v99, v94, v94, 16
	v_bfi_b32 v249, s5, v95, v94
	v_cndmask_b32_e32 v99, v99, v249, vcc
	v_alignbit_b32 v100, v93, v93, 16
	v_bfi_b32 v249, s5, v94, v93
	v_cndmask_b32_e32 v100, v100, v249, vcc
	v_alignbit_b32 v101, v92, v92, 16
	v_bfi_b32 v249, s5, v93, v92
	v_cndmask_b32_e32 v101, v101, v249, vcc
	ds_read2_b32 v[92:93], v245 offset1:1
	ds_read2_b32 v[94:95], v245 offset0:2 offset1:3
	ds_read_b32 v96, v245 offset:16
	v_add_u32_e32 v245, 64, v245
	ds_read_b128 v[88:91], v246 offset:7680
	v_add_u32_e32 v246, 0xffffffb0, v246
	s_waitcnt lgkmcnt(4)
	s_nop 1
	v_mfma_f32_32x32x16_bf16 v[2:17], v[98:101], v[240:243], v[2:17]
	v_alignbit_b32 v72, v69, v69, 16
	v_bfi_b32 v249, s5, v70, v69
	v_cndmask_b32_e32 v72, v72, v249, vcc
	v_alignbit_b32 v73, v68, v68, 16
	v_bfi_b32 v249, s5, v69, v68
	v_cndmask_b32_e32 v73, v73, v249, vcc
	v_alignbit_b32 v74, v67, v67, 16
	v_bfi_b32 v249, s5, v68, v67
	v_cndmask_b32_e32 v74, v74, v249, vcc
	v_alignbit_b32 v75, v66, v66, 16
	v_bfi_b32 v249, s5, v67, v66
	v_cndmask_b32_e32 v75, v75, v249, vcc
	s_add_i32 s4, s4, -1
	s_cmp_lg_u32 s4, 0
	s_cbranch_scc1 .Lhy_seg6
	ds_read_b128 v[240:243], v247 offset:7680
	v_add_u32_e32 v247, 0xffffffb0, v247
	s_waitcnt lgkmcnt(1)
	s_nop 1
	v_mfma_f32_32x32x16_bf16 v[2:17], v[72:75], v[88:91], v[2:17]
	v_alignbit_b32 v98, v95, v95, 16
	v_bfi_b32 v249, s5, v96, v95
	v_cndmask_b32_e32 v98, v98, v249, vcc
	v_alignbit_b32 v99, v94, v94, 16
	v_bfi_b32 v249, s5, v95, v94
	v_cndmask_b32_e32 v99, v99, v249, vcc
	v_alignbit_b32 v100, v93, v93, 16
	v_bfi_b32 v249, s5, v94, v93
	v_cndmask_b32_e32 v100, v100, v249, vcc
	v_alignbit_b32 v101, v92, v92, 16
	v_bfi_b32 v249, s5, v93, v92
	v_cndmask_b32_e32 v101, v101, v249, vcc
	s_waitcnt lgkmcnt(0)
	s_nop 1
	v_mfma_f32_32x32x16_bf16 v[2:17], v[98:101], v[240:243], v[2:17]
	s_nop 7
